# strategy 7 (instruction selection): NSA packed v_pk_fma_f32 accumulator inits split into two v_fma_f32 each (87 sites), on top of LN-stat sharing + batched NSA loops
# speedup vs baseline: 1.0072x; 1.0021x over previous
.LBB0_710:
	v_cmp_ge_i32_e64 s[8:9], s13, v76
	s_mov_b64 s[4:5], -1
	s_and_b64 vcc, exec, s[8:9]
	v_add_u32_e32 v77, v58, v56
	s_cbranch_vccz .LBB0_732
	ds_read_b128 v[160:163], v77
	ds_read_b128 v[164:167], v77 offset:64
	ds_read_b128 v[168:171], v77 offset:2304
	ds_read_b128 v[172:175], v77 offset:2368
	ds_read_b128 v[176:179], v77 offset:4608
	ds_read_b128 v[180:183], v77 offset:4672
	ds_read_b128 v[184:187], v77 offset:6912
	ds_read_b128 v[188:191], v77 offset:6976
	v_cvt_f32_i32_e32 v20, v75
	s_mov_b32 s4, 2.0
	s_mov_b32 s5, 0x40400000
	v_mul_f32_e64 v32, -v96, v20
	v_fma_f32 v21, -v96, v20, v60
	v_mov_b32_e32 v20, v32
	v_fmac_f32_e32 v20, 0, v60
	v_fma_f32 v22, v60, s4, v32
	v_fma_f32 v23, v61, s5, v32
	s_mov_b32 s4, 0x41800000
	s_mov_b32 s5, 0x41880000
	s_waitcnt lgkmcnt(7)
	v_mfma_f32_16x16x32_bf16 v[20:23], v[160:163], v[4:7], v[20:23]
	v_fma_f32 v26, v70, s90, v32
	v_fma_f32 v27, v71, s91, v32
	v_fma_f32 v24, v68, s4, v32
	v_fma_f32 v25, v69, s5, v32
	v_fma_f32 v30, v70, s92, v32
	v_fma_f32 v31, v71, s93, v32
	v_fma_f32 v28, v68, s34, v32
	v_fma_f32 v29, v69, s35, v32
	s_waitcnt lgkmcnt(6)
	v_mfma_f32_16x16x32_bf16 v[20:23], v[164:167], v[8:11], v[20:23]
	v_fma_f32 v34, v70, s22, v32
	v_fma_f32 v35, v71, s23, v32
	v_fma_f32 v33, v69, s73, v32
	v_fma_f32 v32, v68, s72, v32
	s_nop 4
	s_nop 0
	v_max3_f32 v78, v20, s36, v21
	s_waitcnt lgkmcnt(5)
	v_mfma_f32_16x16x32_bf16 v[24:27], v[168:171], v[4:7], v[24:27]
	v_max3_f32 v78, v78, v22, v23
	s_waitcnt lgkmcnt(4)
	v_mfma_f32_16x16x32_bf16 v[24:27], v[172:175], v[8:11], v[24:27]
	s_nop 6
	s_nop 0
	v_max3_f32 v78, v78, v24, v25
	s_waitcnt lgkmcnt(3)
	v_mfma_f32_16x16x32_bf16 v[28:31], v[176:179], v[4:7], v[28:31]
	v_max3_f32 v78, v78, v26, v27
	s_waitcnt lgkmcnt(2)
	v_mfma_f32_16x16x32_bf16 v[28:31], v[180:183], v[8:11], v[28:31]
	s_nop 6
	s_nop 0
	v_max3_f32 v78, v78, v28, v29
	s_waitcnt lgkmcnt(1)
	v_mfma_f32_16x16x32_bf16 v[32:35], v[184:187], v[4:7], v[32:35]
	v_max3_f32 v78, v78, v30, v31
	s_waitcnt lgkmcnt(0)
	v_mfma_f32_16x16x32_bf16 v[32:35], v[188:191], v[8:11], v[32:35]
	s_nop 7
	v_max3_f32 v78, v78, v32, v33
	v_max3_f32 v78, v78, v34, v35
	s_cbranch_execz .LBB0_733

.LBB0_723:
	s_xor_b32 s2, s2, -2
	s_add_i32 s2, s2, s12
	s_lshl_b32 s15, s2, 10
	s_or_b32 s8, s15, 0x3f0
	s_cmp_ge_i32 s13, s8
	s_cselect_b64 s[8:9], -1, 0
	s_mov_b64 s[4:5], -1
	s_and_b64 vcc, exec, s[8:9]
	v_add_u32_e32 v77, v57, v56
	s_cbranch_vccz .LBB0_734
	ds_read_b128 v[160:163], v77
	ds_read_b128 v[164:167], v77 offset:64
	ds_read_b128 v[168:171], v77 offset:2304
	ds_read_b128 v[172:175], v77 offset:2368
	ds_read_b128 v[176:179], v77 offset:4608
	ds_read_b128 v[180:183], v77 offset:4672
	ds_read_b128 v[184:187], v77 offset:6912
	ds_read_b128 v[188:191], v77 offset:6976
	v_subrev_u32_e32 v20, s15, v72
	v_cvt_f32_i32_e32 v20, v20
	s_mov_b32 s4, 2.0
	s_mov_b32 s5, 0x40400000
	v_mul_f32_e64 v32, -v96, v20
	v_fma_f32 v21, -v96, v20, v60
	v_mov_b32_e32 v20, v32
	v_fmac_f32_e32 v20, 0, v60
	v_fma_f32 v22, v60, s4, v32
	v_fma_f32 v23, v61, s5, v32
	s_mov_b32 s4, 0x41800000
	s_mov_b32 s5, 0x41880000
	s_waitcnt lgkmcnt(7)
	v_mfma_f32_16x16x32_bf16 v[20:23], v[160:163], v[4:7], v[20:23]
	v_fma_f32 v26, v70, s90, v32
	v_fma_f32 v27, v71, s91, v32
	v_fma_f32 v24, v68, s4, v32
	v_fma_f32 v25, v69, s5, v32
	v_fma_f32 v30, v70, s92, v32
	v_fma_f32 v31, v71, s93, v32
	s_waitcnt lgkmcnt(6)
	v_mfma_f32_16x16x32_bf16 v[20:23], v[164:167], v[8:11], v[20:23]
	v_fma_f32 v28, v68, s34, v32
	v_fma_f32 v29, v69, s35, v32
	v_fma_f32 v34, v70, s22, v32
	v_fma_f32 v35, v71, s23, v32
	s_waitcnt lgkmcnt(5)
	v_mfma_f32_16x16x32_bf16 v[24:27], v[168:171], v[4:7], v[24:27]
	v_fma_f32 v33, v69, s73, v32
	v_fma_f32 v32, v68, s72, v32
	s_nop 0
	s_nop 1
	v_max3_f32 v78, v20, s36, v21
	s_waitcnt lgkmcnt(4)
	v_mfma_f32_16x16x32_bf16 v[24:27], v[172:175], v[8:11], v[24:27]
	v_max3_f32 v78, v78, v22, v23
	s_waitcnt lgkmcnt(3)
	v_mfma_f32_16x16x32_bf16 v[28:31], v[176:179], v[4:7], v[28:31]
	s_nop 2
	s_nop 1
	v_max3_f32 v78, v78, v24, v25
	s_nop 0
	v_max3_f32 v78, v78, v26, v27
	s_waitcnt lgkmcnt(2)
	v_mfma_f32_16x16x32_bf16 v[28:31], v[180:183], v[8:11], v[28:31]
	s_nop 6
	s_nop 0
	v_max3_f32 v78, v78, v28, v29
	s_waitcnt lgkmcnt(1)
	v_mfma_f32_16x16x32_bf16 v[32:35], v[184:187], v[4:7], v[32:35]
	v_max3_f32 v78, v78, v30, v31
	s_waitcnt lgkmcnt(0)
	v_mfma_f32_16x16x32_bf16 v[32:35], v[188:191], v[8:11], v[32:35]
	s_nop 7
	v_max3_f32 v78, v78, v32, v33
	v_max3_f32 v78, v78, v34, v35
	s_cbranch_execz .LBB0_735

.LBB0_733:
	ds_read_b128 v[20:23], v77
	ds_read_b128 v[24:27], v77 offset:64
	ds_read_b128 v[28:31], v77 offset:2304
	ds_read_b128 v[32:35], v77 offset:2368
	v_lshlrev_b32_e32 v78, 4, v73
	ds_read_b128 v[82:85], v77 offset:4608
	ds_read_b128 v[104:107], v77 offset:4672
	s_waitcnt lgkmcnt(5)
	v_mfma_f32_16x16x32_bf16 v[20:23], v[20:23], v[4:7], 0
	v_add_u32_e32 v81, 16, v78
	v_add_u32_e32 v88, v78, v49
	v_add_u32_e32 v91, v81, v38
	s_waitcnt lgkmcnt(3)
	v_mfma_f32_16x16x32_bf16 v[28:31], v[28:31], v[4:7], 0
	v_cvt_f32_u32_e32 v79, v88
	v_cvt_f32_u32_e32 v78, v91
	v_cmp_lt_i32_e32 vcc, -1, v91
	v_mfma_f32_16x16x32_bf16 v[20:23], v[24:27], v[8:11], v[20:23]
	v_add_u32_e32 v91, v81, v3
	s_waitcnt lgkmcnt(2)
	v_mfma_f32_16x16x32_bf16 v[24:27], v[32:35], v[8:11], v[28:31]
	s_nop 2
	ds_read_b128 v[28:31], v77 offset:6912
	ds_read_b128 v[32:35], v77 offset:6976
	v_add_u32_e32 v77, v81, v62
	v_fma_f32 v20, -v96, v78, v20
	v_fma_f32 v21, -v97, v79, v21
	s_waitcnt lgkmcnt(1)
	v_mfma_f32_16x16x32_bf16 v[28:31], v[28:31], v[4:7], 0
	v_cvt_f32_u32_e32 v79, v91
	v_cvt_f32_u32_e32 v78, v77
	v_cndmask_b32_e32 v20, v249, v20, vcc
	v_cmp_lt_i32_e32 vcc, -1, v88
	s_waitcnt lgkmcnt(0)
	v_mfma_f32_16x16x32_bf16 v[32:35], v[32:35], v[8:11], v[28:31]
	v_fma_f32 v22, -v96, v78, v22
	v_fma_f32 v23, -v97, v79, v23
	v_cndmask_b32_e32 v21, v249, v21, vcc
	v_cmp_lt_i32_e32 vcc, -1, v77
	v_add_u32_e32 v31, v81, v40
	v_add_u32_e32 v77, v81, v39
	v_cvt_f32_u32_e32 v29, v77
	v_cvt_f32_u32_e32 v28, v31
	v_cndmask_b32_e32 v22, v249, v22, vcc
	v_cmp_lt_i32_e32 vcc, -1, v91
	v_add_u32_e32 v78, v81, v41
	v_mfma_f32_16x16x32_bf16 v[82:85], v[82:85], v[4:7], 0
	v_cndmask_b32_e32 v23, v249, v23, vcc
	v_cmp_lt_i32_e32 vcc, -1, v31
	v_add_u32_e32 v31, v81, v42
	v_fma_f32 v24, -v96, v28, v24
	v_fma_f32 v25, -v97, v29, v25
	v_cvt_f32_u32_e32 v29, v78
	v_cvt_f32_u32_e32 v28, v31
	v_cndmask_b32_e32 v24, v249, v24, vcc
	v_cmp_lt_i32_e32 vcc, -1, v77
	v_add_u32_e32 v77, v81, v63
	v_mfma_f32_16x16x32_bf16 v[82:85], v[104:107], v[8:11], v[82:85]
	v_cndmask_b32_e32 v25, v249, v25, vcc
	v_cmp_lt_i32_e32 vcc, -1, v31
	v_add_u32_e32 v31, v81, v64
	v_fma_f32 v26, -v96, v28, v26
	v_fma_f32 v27, -v97, v29, v27
	v_cvt_f32_u32_e32 v29, v77
	v_cvt_f32_u32_e32 v28, v31
	v_max3_f32 v30, v20, s36, v21
	v_max3_f32 v30, v30, v22, v23
	v_cndmask_b32_e32 v26, v249, v26, vcc
	v_cmp_lt_i32_e32 vcc, -1, v78
	v_max3_f32 v30, v30, v24, v25
	v_fma_f32 v28, -v96, v28, v82
	v_fma_f32 v29, -v97, v29, v83
	v_cndmask_b32_e32 v27, v249, v27, vcc
	v_add_u32_e32 v79, v81, v66
	v_add_u32_e32 v82, v81, v65
	v_max3_f32 v78, v30, v26, v27
	v_cmp_lt_i32_e32 vcc, -1, v31
	v_cvt_f32_u32_e32 v31, v82
	v_cvt_f32_u32_e32 v30, v79
	v_cndmask_b32_e32 v28, v249, v28, vcc
	v_cmp_lt_i32_e32 vcc, -1, v77
	v_add_u32_e32 v83, v81, v46
	v_fma_f32 v30, -v96, v30, v84
	v_fma_f32 v31, -v97, v31, v85
	v_cndmask_b32_e32 v29, v249, v29, vcc
	v_add_u32_e32 v84, v81, v43
	v_max3_f32 v77, v78, v28, v29
	v_cmp_lt_i32_e32 vcc, -1, v79
	v_cvt_f32_u32_e32 v79, v84
	v_cvt_f32_u32_e32 v78, v83
	v_cndmask_b32_e32 v30, v249, v30, vcc
	v_cmp_lt_i32_e32 vcc, -1, v82
	v_add_u32_e32 v82, v81, v48
	v_add_u32_e32 v81, v81, v47
	v_fma_f32 v32, -v96, v78, v32
	v_fma_f32 v33, -v97, v79, v33
	v_cvt_f32_u32_e32 v79, v81
	v_cvt_f32_u32_e32 v78, v82
	v_cndmask_b32_e32 v31, v249, v31, vcc
	v_cmp_lt_i32_e32 vcc, -1, v83
	v_max3_f32 v77, v77, v30, v31
	v_fma_f32 v34, -v96, v78, v34
	v_fma_f32 v35, -v97, v79, v35
	v_cndmask_b32_e32 v32, v249, v32, vcc
	v_cmp_lt_i32_e32 vcc, -1, v84
	s_nop 1
	v_cndmask_b32_e32 v33, v249, v33, vcc
	v_cmp_lt_i32_e32 vcc, -1, v82
	v_max3_f32 v77, v77, v32, v33
	s_nop 0
	v_cndmask_b32_e32 v34, v249, v34, vcc
	v_cmp_lt_i32_e32 vcc, -1, v81
	s_nop 1
	v_cndmask_b32_e32 v35, v249, v35, vcc
	v_max3_f32 v78, v77, v34, v35
	v_cmp_gt_f32_e32 vcc, v78, v89
	s_cbranch_vccnz .LBB0_713
	s_branch .LBB0_714

.LBB0_735:
	ds_read_b128 v[20:23], v77
	ds_read_b128 v[24:27], v77 offset:64
	ds_read_b128 v[28:31], v77 offset:2304
	ds_read_b128 v[32:35], v77 offset:2368
	ds_read_b128 v[82:85], v77 offset:4608
	ds_read_b128 v[104:107], v77 offset:4672
	s_waitcnt lgkmcnt(5)
	v_mfma_f32_16x16x32_bf16 v[20:23], v[20:23], v[4:7], 0
	s_mul_i32 s2, s2, 0xfffffc0
	v_sub_u32_e32 v78, s2, v98
	v_add_u32_e32 v79, s2, v99
	v_lshlrev_b32_e32 v81, 4, v78
	s_waitcnt lgkmcnt(3)
	v_mfma_f32_16x16x32_bf16 v[28:31], v[28:31], v[4:7], 0
	v_add_u32_e32 v88, v81, v38
	v_lshl_add_u32 v91, v79, 4, v49
	v_cvt_f32_u32_e32 v79, v91
	v_mfma_f32_16x16x32_bf16 v[20:23], v[24:27], v[8:11], v[20:23]
	v_cvt_f32_u32_e32 v78, v88
	v_cmp_lt_i32_e32 vcc, -1, v88
	v_add_u32_e32 v88, v81, v3
	s_waitcnt lgkmcnt(2)
	v_mfma_f32_16x16x32_bf16 v[24:27], v[32:35], v[8:11], v[28:31]
	s_waitcnt lgkmcnt(1)
	v_mfma_f32_16x16x32_bf16 v[28:31], v[82:85], v[4:7], 0
	ds_read_b128 v[32:35], v77 offset:6912
	ds_read_b128 v[82:85], v77 offset:6976
	v_add_u32_e32 v77, v81, v62
	v_fma_f32 v20, -v96, v78, v20
	v_fma_f32 v21, -v97, v79, v21
	s_waitcnt lgkmcnt(1)
	v_mfma_f32_16x16x32_bf16 v[32:35], v[32:35], v[4:7], 0
	v_cvt_f32_u32_e32 v79, v88
	v_cvt_f32_u32_e32 v78, v77
	v_cndmask_b32_e32 v20, v249, v20, vcc
	v_cmp_lt_i32_e32 vcc, -1, v91
	s_waitcnt lgkmcnt(0)
	v_mfma_f32_16x16x32_bf16 v[32:35], v[82:85], v[8:11], v[32:35]
	v_add_u32_e32 v83, v81, v39
	v_cndmask_b32_e32 v21, v249, v21, vcc
	v_cmp_lt_i32_e32 vcc, -1, v77
	v_add_u32_e32 v77, v81, v40
	v_fma_f32 v22, -v96, v78, v22
	v_fma_f32 v23, -v97, v79, v23
	v_cvt_f32_u32_e32 v79, v83
	v_cvt_f32_u32_e32 v78, v77
	v_cndmask_b32_e32 v22, v249, v22, vcc
	v_cmp_lt_i32_e32 vcc, -1, v88
	v_add_u32_e32 v84, v81, v41
	v_fma_f32 v24, -v96, v78, v24
	v_fma_f32 v25, -v97, v79, v25
	v_cndmask_b32_e32 v23, v249, v23, vcc
	v_cmp_lt_i32_e32 vcc, -1, v77
	v_add_u32_e32 v77, v81, v42
	v_cvt_f32_u32_e32 v79, v84
	v_cvt_f32_u32_e32 v78, v77
	v_cndmask_b32_e32 v24, v249, v24, vcc
	v_cmp_lt_i32_e32 vcc, -1, v83
	v_add_u32_e32 v83, v81, v63
	v_mfma_f32_16x16x32_bf16 v[28:31], v[104:107], v[8:11], v[28:31]
	v_cndmask_b32_e32 v25, v249, v25, vcc
	v_cmp_lt_i32_e32 vcc, -1, v77
	v_add_u32_e32 v77, v81, v64
	v_fma_f32 v26, -v96, v78, v26
	v_fma_f32 v27, -v97, v79, v27
	v_cvt_f32_u32_e32 v79, v83
	v_cvt_f32_u32_e32 v78, v77
	v_cndmask_b32_e32 v26, v249, v26, vcc
	v_cmp_lt_i32_e32 vcc, -1, v84
	v_add_u32_e32 v84, v81, v65
	v_fma_f32 v28, -v96, v78, v28
	v_fma_f32 v29, -v97, v79, v29
	v_cndmask_b32_e32 v27, v249, v27, vcc
	v_cmp_lt_i32_e32 vcc, -1, v77
	v_add_u32_e32 v77, v81, v66
	v_cvt_f32_u32_e32 v79, v84
	v_cvt_f32_u32_e32 v78, v77
	v_cndmask_b32_e32 v28, v249, v28, vcc
	v_cmp_lt_i32_e32 vcc, -1, v83
	v_add_u32_e32 v83, v81, v43
	v_fma_f32 v30, -v96, v78, v30
	v_fma_f32 v31, -v97, v79, v31
	v_cndmask_b32_e32 v29, v249, v29, vcc
	v_cmp_lt_i32_e32 vcc, -1, v77
	v_add_u32_e32 v77, v81, v46
	v_cvt_f32_u32_e32 v79, v83
	v_cvt_f32_u32_e32 v78, v77
	v_cndmask_b32_e32 v30, v249, v30, vcc
	v_cmp_lt_i32_e32 vcc, -1, v84
	v_max3_f32 v82, v20, s36, v21
	v_fma_f32 v32, -v96, v78, v32
	v_fma_f32 v33, -v97, v79, v33
	v_cndmask_b32_e32 v31, v249, v31, vcc
	v_cmp_lt_i32_e32 vcc, -1, v77
	v_add_u32_e32 v77, v81, v48
	v_add_u32_e32 v81, v81, v47
	v_cvt_f32_u32_e32 v79, v81
	v_cvt_f32_u32_e32 v78, v77
	v_max3_f32 v82, v82, v22, v23
	v_max3_f32 v82, v82, v24, v25
	v_max3_f32 v82, v82, v26, v27
	v_cndmask_b32_e32 v32, v249, v32, vcc
	v_cmp_lt_i32_e32 vcc, -1, v83
	v_max3_f32 v82, v82, v28, v29
	v_fma_f32 v34, -v96, v78, v34
	v_fma_f32 v35, -v97, v79, v35
	v_cndmask_b32_e32 v33, v249, v33, vcc
	v_cmp_lt_i32_e32 vcc, -1, v77
	v_max3_f32 v82, v82, v30, v31
	v_max3_f32 v82, v82, v32, v33
	v_cndmask_b32_e32 v34, v249, v34, vcc
	v_cmp_lt_i32_e32 vcc, -1, v81
	s_nop 1
	v_cndmask_b32_e32 v35, v249, v35, vcc
	v_max3_f32 v78, v82, v34, v35
	v_cmp_gt_f32_e32 vcc, v78, v89
	s_cbranch_vccnz .LBB0_726
	s_branch .LBB0_727

.LBB0_745:
	s_add_i32 s2, s16, 0xfffffc00
	s_cmp_ge_i32 s13, s2
	s_cselect_b64 s[4:5], -1, 0
	s_cmp_lt_i32 s13, s2
	s_cbranch_scc1 .Lp2_zero_e
	s_movk_i32 s2, 0x3c1
	v_add3_u32 v44, v81, v90, s2
	v_cvt_f32_i32_e32 v44, v44
	s_mov_b32 s6, 2.0
	s_mov_b32 s7, 0x40400000
	v_fma_f32 v48, -v96, v44, -v89
	v_fma_f32 v54, v60, s6, v48
	v_fma_f32 v55, v61, s7, v48
	s_mov_b32 s6, 0x41800000
	s_mov_b32 s7, 0x41880000
	v_fma_f32 v52, 0, v60, v48
	v_add_f32_e32 v53, v60, v48
	v_fma_f32 v58, v70, s90, v48
	v_fma_f32 v59, v71, s91, v48
	v_fma_f32 v56, v68, s6, v48
	v_fma_f32 v57, v69, s7, v48
	v_fma_f32 v46, v70, s92, v48
	v_fma_f32 v47, v71, s93, v48
	v_fma_f32 v44, v68, s34, v48
	v_fma_f32 v45, v69, s35, v48
	v_fma_f32 v50, v70, s22, v48
	v_fma_f32 v51, v71, s23, v48
	v_fma_f32 v49, v69, s73, v48
	v_fma_f32 v48, v68, s72, v48

.LBB0_764:
	s_cmp_ge_i32 s13, s16
	s_cselect_b64 s[4:5], -1, 0
	s_cmp_lt_i32 s13, s16
	s_cbranch_scc1 .Lp2_zero_o
	s_movk_i32 s2, 0xffc1
	v_add3_u32 v44, v81, v90, s2
	v_cvt_f32_i32_e32 v44, v44
	s_mov_b32 s6, 2.0
	s_mov_b32 s7, 0x40400000
	v_fma_f32 v48, -v96, v44, -v89
	v_fma_f32 v54, v60, s6, v48
	v_fma_f32 v55, v61, s7, v48
	s_mov_b32 s6, 0x41800000
	s_mov_b32 s7, 0x41880000
	v_fma_f32 v52, 0, v60, v48
	v_add_f32_e32 v53, v60, v48
	v_fma_f32 v58, v70, s90, v48
	v_fma_f32 v59, v71, s91, v48
	v_fma_f32 v56, v68, s6, v48
	v_fma_f32 v57, v69, s7, v48
	v_fma_f32 v46, v70, s92, v48
	v_fma_f32 v47, v71, s93, v48
	v_fma_f32 v44, v68, s34, v48
	v_fma_f32 v45, v69, s35, v48
	v_fma_f32 v50, v70, s22, v48
	v_fma_f32 v51, v71, s23, v48
	v_fma_f32 v49, v69, s73, v48
	v_fma_f32 v48, v68, s72, v48

.LBB0_977:
	s_and_b64 vcc, exec, s[4:5]
	s_cbranch_vccz .LBB0_981
	s_nop 5
	v_or_b32_e32 v60, v98, v108
	v_sub_u32_e32 v60, v103, v60
	v_cvt_f32_i32_e32 v60, v60
	s_mov_b32 s4, 2.0
	s_mov_b32 s5, 0x40400000
	v_fma_f32 v60, -v96, v60, -v106
	v_cndmask_b32_e64 v68, v249, v60, s[8:9]
	v_fma_f32 v62, v96, s4, v68
	v_fma_f32 v63, v97, s5, v68
	s_mov_b32 s4, 0x41800000
	s_mov_b32 s5, 0x41880000
	v_fma_f32 v60, 0, v96, v68
	v_add_f32_e32 v61, v96, v68
	v_fma_f32 v66, v90, s90, v68
	v_fma_f32 v67, v91, s91, v68
	v_fma_f32 v64, v88, s4, v68
	v_fma_f32 v65, v89, s5, v68
	v_fma_f32 v78, v90, s92, v68
	v_fma_f32 v79, v91, s93, v68
	v_fma_f32 v76, v88, s34, v68
	v_fma_f32 v77, v89, s35, v68
	v_fma_f32 v110, v90, s22, v68
	v_fma_f32 v111, v91, s23, v68
	v_fma_f32 v108, v88, s72, v68
	v_fma_f32 v109, v89, s73, v68
	s_waitcnt lgkmcnt(7)
	v_mfma_f32_16x16x32_bf16 v[60:63], v[160:163], v[4:7], v[60:63]
	s_waitcnt lgkmcnt(6)
	v_mfma_f32_16x16x32_bf16 v[72:75], v[164:167], v[8:11], v[60:63]
	ds_read_b128 v[196:199], v243
	ds_read_b128 v[200:203], v243 offset:64
	s_waitcnt lgkmcnt(7)
	v_mfma_f32_16x16x32_bf16 v[60:63], v[168:171], v[4:7], v[64:67]
	s_waitcnt lgkmcnt(6)
	v_mfma_f32_16x16x32_bf16 v[68:71], v[172:175], v[8:11], v[60:63]
	ds_read_b128 v[204:207], v243 offset:2304
	ds_read_b128 v[208:211], v243 offset:2368
	s_waitcnt lgkmcnt(7)
	v_mfma_f32_16x16x32_bf16 v[60:63], v[176:179], v[4:7], v[76:79]
	s_waitcnt lgkmcnt(6)
	v_mfma_f32_16x16x32_bf16 v[60:63], v[180:183], v[8:11], v[60:63]
	ds_read_b128 v[212:215], v243 offset:4608
	ds_read_b128 v[216:219], v243 offset:4672
	s_waitcnt lgkmcnt(7)
	v_mfma_f32_16x16x32_bf16 v[64:67], v[184:187], v[4:7], v[108:111]
	s_waitcnt lgkmcnt(6)
	v_mfma_f32_16x16x32_bf16 v[64:67], v[188:191], v[8:11], v[64:67]
	ds_read_b128 v[220:223], v243 offset:6912
	ds_read_b128 v[224:227], v243 offset:6976
	v_max3_f32 v76, v72, s36, v73
	v_max3_f32 v76, v76, v74, v75
	v_max3_f32 v76, v76, v68, v69
	v_max3_f32 v76, v76, v70, v71
	v_max3_f32 v76, v76, v60, v61
	v_max3_f32 v76, v76, v62, v63
	s_nop 1
	v_max3_f32 v76, v76, v64, v65
	v_max3_f32 v76, v76, v66, v67
	v_cmp_lt_f32_e32 vcc, 0, v76
	s_cbranch_vccz .LBB0_980
	ds_bpermute_b32 v77, v115, v76
	v_max_f32_e32 v76, v76, v76
	s_waitcnt lgkmcnt(0)
	v_max_f32_e32 v77, v77, v77
	v_max_f32_e32 v76, v76, v77
	ds_bpermute_b32 v77, v114, v76
	s_waitcnt lgkmcnt(0)
	v_max3_f32 v77, 0, v76, v77
	v_sub_f32_e32 v76, 0, v77
	v_exp_f32_e32 v76, v76
	v_add_f32_e32 v106, v106, v77
	v_mul_f32_e32 v107, v107, v76
	v_pk_mul_f32 v[42:43], v[42:43], v[76:77] op_sel_hi:[1,0]
	v_pk_mul_f32 v[40:41], v[40:41], v[76:77] op_sel_hi:[1,0]
	v_pk_mul_f32 v[38:39], v[38:39], v[76:77] op_sel_hi:[1,0]
	v_pk_mul_f32 v[36:37], v[36:37], v[76:77] op_sel_hi:[1,0]
	v_pk_mul_f32 v[34:35], v[34:35], v[76:77] op_sel_hi:[1,0]
	v_pk_mul_f32 v[32:33], v[32:33], v[76:77] op_sel_hi:[1,0]
	v_pk_mul_f32 v[30:31], v[30:31], v[76:77] op_sel_hi:[1,0]
	v_pk_mul_f32 v[28:29], v[28:29], v[76:77] op_sel_hi:[1,0]
	v_sub_f32_e32 v72, v72, v77
	v_sub_f32_e32 v73, v73, v77
	v_sub_f32_e32 v74, v74, v77
	v_sub_f32_e32 v75, v75, v77
	v_sub_f32_e32 v68, v68, v77
	v_sub_f32_e32 v69, v69, v77
	v_sub_f32_e32 v70, v70, v77
	v_sub_f32_e32 v71, v71, v77
	v_sub_f32_e32 v60, v60, v77
	v_sub_f32_e32 v61, v61, v77
	v_sub_f32_e32 v62, v62, v77
	v_sub_f32_e32 v63, v63, v77
	v_sub_f32_e32 v64, v64, v77
	v_sub_f32_e32 v65, v65, v77
	v_sub_f32_e32 v66, v66, v77
	v_sub_f32_e32 v67, v67, v77

.LBB0_992:
	s_and_b64 vcc, exec, s[4:5]
	s_cbranch_vccz .LBB0_996
	s_nop 5
	v_or_b32_e32 v60, v98, v108
	v_sub_u32_e32 v60, v103, v60
	v_cvt_f32_i32_e32 v60, v60
	s_mov_b32 s4, 2.0
	s_mov_b32 s5, 0x40400000
	v_fma_f32 v60, -v96, v60, -v106
	v_cndmask_b32_e64 v68, v249, v60, s[8:9]
	v_fma_f32 v62, v96, s4, v68
	v_fma_f32 v63, v97, s5, v68
	s_mov_b32 s4, 0x41800000
	s_mov_b32 s5, 0x41880000
	v_fma_f32 v60, 0, v96, v68
	v_add_f32_e32 v61, v96, v68
	v_fma_f32 v66, v90, s90, v68
	v_fma_f32 v67, v91, s91, v68
	v_fma_f32 v64, v88, s4, v68
	v_fma_f32 v65, v89, s5, v68
	v_fma_f32 v78, v90, s92, v68
	v_fma_f32 v79, v91, s93, v68
	v_fma_f32 v76, v88, s34, v68
	v_fma_f32 v77, v89, s35, v68
	v_fma_f32 v110, v90, s22, v68
	v_fma_f32 v111, v91, s23, v68
	v_fma_f32 v108, v88, s72, v68
	v_fma_f32 v109, v89, s73, v68
	s_waitcnt lgkmcnt(7)
	v_mfma_f32_16x16x32_bf16 v[60:63], v[160:163], v[4:7], v[60:63]
	s_waitcnt lgkmcnt(6)
	v_mfma_f32_16x16x32_bf16 v[72:75], v[164:167], v[8:11], v[60:63]
	ds_read_b128 v[196:199], v244
	ds_read_b128 v[200:203], v244 offset:64
	s_waitcnt lgkmcnt(7)
	v_mfma_f32_16x16x32_bf16 v[60:63], v[168:171], v[4:7], v[64:67]
	s_waitcnt lgkmcnt(6)
	v_mfma_f32_16x16x32_bf16 v[68:71], v[172:175], v[8:11], v[60:63]
	ds_read_b128 v[204:207], v244 offset:2304
	ds_read_b128 v[208:211], v244 offset:2368
	s_waitcnt lgkmcnt(7)
	v_mfma_f32_16x16x32_bf16 v[60:63], v[176:179], v[4:7], v[76:79]
	s_waitcnt lgkmcnt(6)
	v_mfma_f32_16x16x32_bf16 v[60:63], v[180:183], v[8:11], v[60:63]
	ds_read_b128 v[212:215], v244 offset:4608
	ds_read_b128 v[216:219], v244 offset:4672
	s_waitcnt lgkmcnt(7)
	v_mfma_f32_16x16x32_bf16 v[64:67], v[184:187], v[4:7], v[108:111]
	s_waitcnt lgkmcnt(6)
	v_mfma_f32_16x16x32_bf16 v[64:67], v[188:191], v[8:11], v[64:67]
	ds_read_b128 v[220:223], v244 offset:6912
	ds_read_b128 v[224:227], v244 offset:6976
	v_max3_f32 v76, v72, s36, v73
	v_max3_f32 v76, v76, v74, v75
	v_max3_f32 v76, v76, v68, v69
	v_max3_f32 v76, v76, v70, v71
	v_max3_f32 v76, v76, v60, v61
	v_max3_f32 v76, v76, v62, v63
	s_nop 1
	v_max3_f32 v76, v76, v64, v65
	v_max3_f32 v76, v76, v66, v67
	v_cmp_lt_f32_e32 vcc, 0, v76
	s_cbranch_vccz .LBB0_995
	ds_bpermute_b32 v77, v115, v76
	v_max_f32_e32 v76, v76, v76
	s_waitcnt lgkmcnt(0)
	v_max_f32_e32 v77, v77, v77
	v_max_f32_e32 v76, v76, v77
	ds_bpermute_b32 v77, v114, v76
	s_waitcnt lgkmcnt(0)
	v_max3_f32 v77, 0, v76, v77
	v_sub_f32_e32 v76, 0, v77
	v_exp_f32_e32 v76, v76
	v_add_f32_e32 v106, v106, v77
	v_mul_f32_e32 v107, v107, v76
	v_pk_mul_f32 v[42:43], v[42:43], v[76:77] op_sel_hi:[1,0]
	v_pk_mul_f32 v[40:41], v[40:41], v[76:77] op_sel_hi:[1,0]
	v_pk_mul_f32 v[38:39], v[38:39], v[76:77] op_sel_hi:[1,0]
	v_pk_mul_f32 v[36:37], v[36:37], v[76:77] op_sel_hi:[1,0]
	v_pk_mul_f32 v[34:35], v[34:35], v[76:77] op_sel_hi:[1,0]
	v_pk_mul_f32 v[32:33], v[32:33], v[76:77] op_sel_hi:[1,0]
	v_pk_mul_f32 v[30:31], v[30:31], v[76:77] op_sel_hi:[1,0]
	v_pk_mul_f32 v[28:29], v[28:29], v[76:77] op_sel_hi:[1,0]
	v_sub_f32_e32 v72, v72, v77
	v_sub_f32_e32 v73, v73, v77
	v_sub_f32_e32 v74, v74, v77
	v_sub_f32_e32 v75, v75, v77
	v_sub_f32_e32 v68, v68, v77
	v_sub_f32_e32 v69, v69, v77
	v_sub_f32_e32 v70, v70, v77
	v_sub_f32_e32 v71, v71, v77
	v_sub_f32_e32 v60, v60, v77
	v_sub_f32_e32 v61, v61, v77
	v_sub_f32_e32 v62, v62, v77
	v_sub_f32_e32 v63, v63, v77
	v_sub_f32_e32 v64, v64, v77
	v_sub_f32_e32 v65, v65, v77
	v_sub_f32_e32 v66, v66, v77
	v_sub_f32_e32 v67, v67, v77

.LBB0_1010:
	s_add_i32 s1, s14, s0
	s_addk_i32 s1, 0xc0
	s_cmp_ge_i32 s44, s1
	s_cselect_b64 s[4:5], -1, 0
	s_add_i32 s1, s43, s15
	s_cmpk_lt_i32 s1, 0x200
	s_cselect_b64 s[20:21], -1, 0
	s_and_b64 s[4:5], s[4:5], s[20:21]
	s_andn2_b64 vcc, exec, s[4:5]
	s_mov_b64 s[4:5], -1
	s_cbranch_vccz .LBB0_1024
	ds_read_b128 v[76:79], v118
	ds_read_b128 v[80:83], v118 offset:64
	ds_read_b128 v[84:87], v118 offset:2304
	ds_read_b128 v[88:91], v118 offset:2368
	v_add_u32_e32 v0, s43, v125
	s_waitcnt lgkmcnt(3)
	v_mfma_f32_16x16x32_bf16 v[76:79], v[76:79], v[4:7], 0
	ds_read_b128 v[128:131], v118 offset:4608
	ds_read_b128 v[132:135], v118 offset:4672
	v_sub_u32_e32 v146, v0, v98
	v_add_u32_e32 v136, v0, v99
	s_waitcnt lgkmcnt(4)
	v_mfma_f32_16x16x32_bf16 v[76:79], v[80:83], v[8:11], v[76:79]
	v_cvt_f32_u32_e32 v3, v136
	v_cvt_f32_u32_e32 v2, v146
	v_cmp_gt_u32_e32 vcc, s83, v136
	s_waitcnt lgkmcnt(3)
	v_mfma_f32_16x16x32_bf16 v[84:87], v[84:87], v[4:7], 0
	v_sub_u32_e32 v136, v0, v101
	v_sub_u32_e32 v0, v0, v102
	s_nop 0
	v_fma_f32 v2, -v96, v2, v76
	v_fma_f32 v3, -v97, v3, v77
	s_waitcnt lgkmcnt(2)
	v_mfma_f32_16x16x32_bf16 v[80:83], v[88:91], v[8:11], v[84:87]
	s_nop 2
	ds_read_b128 v[84:87], v118 offset:6912
	ds_read_b128 v[88:91], v118 offset:6976
	v_cvt_f32_u32_e32 v77, v136
	v_cvt_f32_u32_e32 v76, v0
	s_waitcnt lgkmcnt(1)
	v_mfma_f32_16x16x32_bf16 v[84:87], v[84:87], v[4:7], 0
	v_cndmask_b32_e32 v3, v249, v3, vcc
	v_cmp_gt_u32_e32 vcc, s83, v146
	v_fma_f32 v76, -v96, v76, v78
	v_fma_f32 v77, -v97, v77, v79
	v_mfma_f32_16x16x32_bf16 v[128:131], v[128:131], v[4:7], 0
	s_waitcnt lgkmcnt(0)
	v_mfma_f32_16x16x32_bf16 v[84:87], v[88:91], v[8:11], v[84:87]
	v_subrev_u32_e32 v88, 17, v146
	v_add_u32_e32 v89, -16, v146
	v_cvt_f32_u32_e32 v79, v88
	v_cvt_f32_u32_e32 v78, v89
	v_mfma_f32_16x16x32_bf16 v[142:145], v[132:135], v[8:11], v[128:131]
	s_nop 2
	v_cndmask_b32_e32 v130, v249, v2, vcc
	v_cmp_gt_u32_e32 vcc, s83, v136
	v_max3_f32 v2, v130, s36, v3
	s_nop 0
	v_cndmask_b32_e32 v128, v249, v77, vcc
	v_cmp_gt_u32_e32 vcc, s83, v0
	s_nop 1
	v_cndmask_b32_e32 v135, v249, v76, vcc
	v_max3_f32 v0, v2, v135, v128
	v_fma_f32 v76, -v96, v78, v80
	v_fma_f32 v77, -v97, v79, v81
	v_subrev_u32_e32 v2, 19, v146
	v_subrev_u32_e32 v80, 18, v146
	v_cvt_f32_u32_e32 v79, v2
	v_cvt_f32_u32_e32 v78, v80
	v_cmp_gt_u32_e32 vcc, s83, v88
	v_subrev_u32_e32 v81, 32, v146
	s_nop 0
	v_cndmask_b32_e32 v129, v249, v77, vcc
	v_cmp_gt_u32_e32 vcc, s83, v89
	v_mov_b64_e32 v[90:91], v[74:75]
	v_mov_b64_e32 v[88:89], v[72:73]
	v_cndmask_b32_e32 v137, v249, v76, vcc
	v_cmp_gt_u32_e32 vcc, s83, v2
	v_subrev_u32_e32 v2, 33, v146
	v_fma_f32 v76, -v96, v78, v82
	v_fma_f32 v77, -v97, v79, v83
	v_cvt_f32_u32_e32 v79, v2
	v_cvt_f32_u32_e32 v78, v81
	v_cndmask_b32_e32 v134, v249, v77, vcc
	v_cmp_gt_u32_e32 vcc, s83, v80
	v_subrev_u32_e32 v80, 34, v146
	v_max3_f32 v0, v0, v137, v129
	v_cndmask_b32_e32 v140, v249, v76, vcc
	v_cmp_gt_u32_e32 vcc, s83, v2
	v_subrev_u32_e32 v2, 35, v146
	v_fma_f32 v76, -v96, v78, v142
	v_fma_f32 v77, -v97, v79, v143
	v_cvt_f32_u32_e32 v79, v2
	v_cvt_f32_u32_e32 v78, v80
	v_cndmask_b32_e32 v131, v249, v77, vcc
	v_cmp_gt_u32_e32 vcc, s83, v81
	v_subrev_u32_e32 v81, 48, v146
	v_max3_f32 v0, v0, v140, v134
	v_cndmask_b32_e32 v139, v249, v76, vcc
	v_cmp_gt_u32_e32 vcc, s83, v2
	v_subrev_u32_e32 v2, 49, v146
	v_fma_f32 v76, -v96, v78, v144
	v_fma_f32 v77, -v97, v79, v145
	v_cvt_f32_u32_e32 v79, v2
	v_cvt_f32_u32_e32 v78, v81
	v_cndmask_b32_e32 v136, v249, v77, vcc
	v_cmp_gt_u32_e32 vcc, s83, v80
	v_subrev_u32_e32 v80, 50, v146
	v_max3_f32 v0, v0, v139, v131
	v_cndmask_b32_e32 v141, v249, v76, vcc
	v_cmp_gt_u32_e32 vcc, s83, v2
	v_subrev_u32_e32 v2, 51, v146
	v_fma_f32 v76, -v96, v78, v84
	v_fma_f32 v77, -v97, v79, v85
	v_cvt_f32_u32_e32 v79, v2
	v_cvt_f32_u32_e32 v78, v80
	v_cndmask_b32_e32 v138, v249, v77, vcc
	v_cmp_gt_u32_e32 vcc, s83, v81
	v_max3_f32 v0, v0, v141, v136
	s_nop 0
	v_cndmask_b32_e32 v142, v249, v76, vcc
	v_fma_f32 v76, -v96, v78, v86
	v_fma_f32 v77, -v97, v79, v87
	v_cmp_gt_u32_e32 vcc, s83, v2
	v_max3_f32 v0, v0, v142, v138
	v_mov_b64_e32 v[86:87], v[70:71]
	v_cndmask_b32_e32 v133, v249, v77, vcc
	v_cmp_gt_u32_e32 vcc, s83, v80
	v_mov_b64_e32 v[82:83], v[66:67]
	v_mov_b64_e32 v[84:85], v[68:69]
	v_cndmask_b32_e32 v132, v249, v76, vcc
	v_max3_f32 v143, v0, v132, v133
	v_mov_b64_e32 v[78:79], v[62:63]
	v_cmp_gt_f32_e32 vcc, v143, v126
	v_mov_b64_e32 v[80:81], v[64:65]
	v_mov_b64_e32 v[76:77], v[60:61]
	v_mov_b32_e32 v2, v127
	v_mov_b32_e32 v0, v126
	s_cbranch_vccz .LBB0_1013
	ds_bpermute_b32 v0, v115, v143
	v_max_f32_e32 v2, v143, v143
	s_waitcnt lgkmcnt(0)
	v_max_f32_e32 v0, v0, v0
	v_max_f32_e32 v0, v2, v0
	ds_bpermute_b32 v2, v114, v0
	s_waitcnt lgkmcnt(0)
	v_max3_f32 v0, v126, v0, v2
	v_sub_f32_e32 v2, v126, v0
	v_exp_f32_e32 v88, v2
	s_nop 0
	v_mul_f32_e32 v2, v127, v88
	v_pk_mul_f32 v[78:79], v[62:63], v[88:89] op_sel_hi:[1,0]
	v_pk_mul_f32 v[76:77], v[60:61], v[88:89] op_sel_hi:[1,0]
	v_pk_mul_f32 v[82:83], v[66:67], v[88:89] op_sel_hi:[1,0]
	v_pk_mul_f32 v[80:81], v[64:65], v[88:89] op_sel_hi:[1,0]
	v_pk_mul_f32 v[86:87], v[70:71], v[88:89] op_sel_hi:[1,0]
	v_pk_mul_f32 v[84:85], v[68:69], v[88:89] op_sel_hi:[1,0]
	v_pk_mul_f32 v[90:91], v[74:75], v[88:89] op_sel_hi:[1,0]
	v_pk_mul_f32 v[88:89], v[72:73], v[88:89] op_sel_hi:[1,0]

.LBB0_1019:
	s_xor_b32 s1, s17, 0x3fffffe
	s_add_i32 s1, s1, s10
	s_lshl_b32 s1, s1, 6
	s_add_i32 s1, s1, s88
	s_or_b32 s2, s1, 63
	s_cmp_ge_i32 s44, s2
	s_cselect_b64 s[4:5], -1, 0
	s_sub_i32 s2, s13, s1
	s_cmpk_lt_i32 s2, 0x200
	s_cselect_b64 s[20:21], -1, 0
	s_and_b64 s[4:5], s[4:5], s[20:21]
	s_andn2_b64 vcc, exec, s[4:5]
	s_mov_b64 s[4:5], -1
	s_cbranch_vccz .LBB0_1029
	ds_read_b128 v[60:63], v119
	ds_read_b128 v[64:67], v119 offset:64
	ds_read_b128 v[68:71], v119 offset:2304
	ds_read_b128 v[72:75], v119 offset:2368
	v_subrev_u32_e32 v3, s1, v103
	s_waitcnt lgkmcnt(3)
	v_mfma_f32_16x16x32_bf16 v[60:63], v[60:63], v[4:7], 0
	v_sub_u32_e32 v146, v3, v98
	v_add_u32_e32 v138, v3, v99
	ds_read_b128 v[126:129], v119 offset:4608
	ds_read_b128 v[130:133], v119 offset:4672
	s_waitcnt lgkmcnt(4)
	v_mfma_f32_16x16x32_bf16 v[60:63], v[64:67], v[8:11], v[60:63]
	v_cvt_f32_u32_e32 v135, v138
	v_cvt_f32_u32_e32 v134, v146
	v_cmp_gt_u32_e32 vcc, s83, v138
	s_waitcnt lgkmcnt(3)
	v_mfma_f32_16x16x32_bf16 v[68:71], v[68:71], v[4:7], 0
	s_waitcnt lgkmcnt(2)
	v_mfma_f32_16x16x32_bf16 v[64:67], v[72:75], v[8:11], v[68:71]
	s_nop 5
	ds_read_b128 v[68:71], v119 offset:6912
	ds_read_b128 v[72:75], v119 offset:6976
	v_fma_f32 v60, -v96, v134, v60
	v_fma_f32 v61, -v97, v135, v61
	s_waitcnt lgkmcnt(3)
	v_mfma_f32_16x16x32_bf16 v[134:137], v[126:129], v[4:7], 0
	v_sub_u32_e32 v126, v3, v101
	v_sub_u32_e32 v3, v3, v102
	v_cvt_f32_u32_e32 v129, v126
	s_waitcnt lgkmcnt(1)
	v_mfma_f32_16x16x32_bf16 v[68:71], v[68:71], v[4:7], 0
	v_cvt_f32_u32_e32 v128, v3
	v_cndmask_b32_e32 v127, v249, v61, vcc
	v_cmp_gt_u32_e32 vcc, s83, v146
	s_waitcnt lgkmcnt(0)
	v_mfma_f32_16x16x32_bf16 v[68:71], v[72:75], v[8:11], v[68:71]
	v_subrev_u32_e32 v72, 17, v146
	v_add_u32_e32 v73, -16, v146
	v_mfma_f32_16x16x32_bf16 v[142:145], v[130:133], v[8:11], v[134:137]
	v_cndmask_b32_e32 v130, v249, v60, vcc
	v_fma_f32 v60, -v96, v128, v62
	v_fma_f32 v61, -v97, v129, v63
	v_cvt_f32_u32_e32 v63, v72
	v_cvt_f32_u32_e32 v62, v73
	v_cmp_gt_u32_e32 vcc, s83, v126
	v_max3_f32 v131, v130, s36, v127
	v_mov_b32_e32 v126, v0
	v_cndmask_b32_e32 v128, v249, v61, vcc
	v_cmp_gt_u32_e32 vcc, s83, v3
	s_nop 1
	v_cndmask_b32_e32 v135, v249, v60, vcc
	v_fma_f32 v60, -v96, v62, v64
	v_fma_f32 v61, -v97, v63, v65
	v_subrev_u32_e32 v64, 19, v146
	v_subrev_u32_e32 v65, 18, v146
	v_cvt_f32_u32_e32 v63, v64
	v_cvt_f32_u32_e32 v62, v65
	v_cmp_gt_u32_e32 vcc, s83, v72
	v_max3_f32 v3, v131, v135, v128
	s_nop 0
	v_cndmask_b32_e32 v129, v249, v61, vcc
	v_cmp_gt_u32_e32 vcc, s83, v73
	v_mov_b64_e32 v[72:73], v[88:89]
	v_mov_b64_e32 v[74:75], v[90:91]
	v_cndmask_b32_e32 v137, v249, v60, vcc
	v_fma_f32 v60, -v96, v62, v66
	v_fma_f32 v61, -v97, v63, v67
	v_cmp_gt_u32_e32 vcc, s83, v64
	v_subrev_u32_e32 v64, 33, v146
	v_subrev_u32_e32 v66, 32, v146
	v_cvt_f32_u32_e32 v63, v64
	v_cvt_f32_u32_e32 v62, v66
	v_cndmask_b32_e32 v134, v249, v61, vcc
	v_cmp_gt_u32_e32 vcc, s83, v65
	v_subrev_u32_e32 v65, 34, v146
	v_max3_f32 v3, v3, v137, v129
	v_cndmask_b32_e32 v140, v249, v60, vcc
	v_cmp_gt_u32_e32 vcc, s83, v64
	v_subrev_u32_e32 v64, 35, v146
	v_fma_f32 v60, -v96, v62, v142
	v_fma_f32 v61, -v97, v63, v143
	v_cvt_f32_u32_e32 v63, v64
	v_cvt_f32_u32_e32 v62, v65
	v_cndmask_b32_e32 v131, v249, v61, vcc
	v_cmp_gt_u32_e32 vcc, s83, v66
	v_subrev_u32_e32 v66, 48, v146
	v_max3_f32 v3, v3, v140, v134
	v_cndmask_b32_e32 v139, v249, v60, vcc
	v_cmp_gt_u32_e32 vcc, s83, v64
	v_subrev_u32_e32 v64, 49, v146
	v_fma_f32 v60, -v96, v62, v144
	v_fma_f32 v61, -v97, v63, v145
	v_cvt_f32_u32_e32 v63, v64
	v_cvt_f32_u32_e32 v62, v66
	v_cndmask_b32_e32 v136, v249, v61, vcc
	v_cmp_gt_u32_e32 vcc, s83, v65
	v_subrev_u32_e32 v65, 50, v146
	v_max3_f32 v3, v3, v139, v131
	v_cndmask_b32_e32 v141, v249, v60, vcc
	v_cmp_gt_u32_e32 vcc, s83, v64
	v_subrev_u32_e32 v64, 51, v146
	v_fma_f32 v60, -v96, v62, v68
	v_fma_f32 v61, -v97, v63, v69
	v_cvt_f32_u32_e32 v63, v64
	v_cvt_f32_u32_e32 v62, v65
	v_cndmask_b32_e32 v138, v249, v61, vcc
	v_cmp_gt_u32_e32 vcc, s83, v66
	v_max3_f32 v3, v3, v141, v136
	s_nop 0
	v_cndmask_b32_e32 v142, v249, v60, vcc
	v_fma_f32 v60, -v96, v62, v70
	v_fma_f32 v61, -v97, v63, v71
	v_cmp_gt_u32_e32 vcc, s83, v64
	v_max3_f32 v3, v3, v142, v138
	v_mov_b64_e32 v[68:69], v[84:85]
	v_cndmask_b32_e32 v133, v249, v61, vcc
	v_cmp_gt_u32_e32 vcc, s83, v65
	v_mov_b64_e32 v[64:65], v[80:81]
	v_mov_b64_e32 v[70:71], v[86:87]
	v_cndmask_b32_e32 v132, v249, v60, vcc
	v_max3_f32 v143, v3, v132, v133
	v_mov_b64_e32 v[60:61], v[76:77]
	v_cmp_gt_f32_e32 vcc, v143, v0
	v_mov_b64_e32 v[66:67], v[82:83]
	v_mov_b64_e32 v[62:63], v[78:79]
	v_mov_b32_e32 v3, v2
	s_cbranch_vccz .LBB0_1022
	ds_bpermute_b32 v3, v115, v143
	v_max_f32_e32 v60, v143, v143
	s_waitcnt lgkmcnt(0)
	v_max_f32_e32 v3, v3, v3
	v_max_f32_e32 v3, v60, v3
	ds_bpermute_b32 v60, v114, v3
	s_waitcnt lgkmcnt(0)
	v_max3_f32 v126, v0, v3, v60
	v_sub_f32_e32 v3, v0, v126
	v_exp_f32_e32 v72, v3
	s_nop 0
	v_mul_f32_e32 v3, v2, v72
	v_pk_mul_f32 v[62:63], v[78:79], v[72:73] op_sel_hi:[1,0]
	v_pk_mul_f32 v[60:61], v[76:77], v[72:73] op_sel_hi:[1,0]
	v_pk_mul_f32 v[66:67], v[82:83], v[72:73] op_sel_hi:[1,0]
	v_pk_mul_f32 v[64:65], v[80:81], v[72:73] op_sel_hi:[1,0]
	v_pk_mul_f32 v[70:71], v[86:87], v[72:73] op_sel_hi:[1,0]
	v_pk_mul_f32 v[68:69], v[84:85], v[72:73] op_sel_hi:[1,0]
	v_pk_mul_f32 v[74:75], v[90:91], v[72:73] op_sel_hi:[1,0]
	v_pk_mul_f32 v[72:73], v[88:89], v[72:73] op_sel_hi:[1,0]

.LBB0_1024:
	s_and_b64 vcc, exec, s[4:5]
	s_cbranch_vccz .LBB0_1014
	ds_read_b128 v[160:163], v118
	ds_read_b128 v[164:167], v118 offset:64
	ds_read_b128 v[168:171], v118 offset:2304
	ds_read_b128 v[172:175], v118 offset:2368
	ds_read_b128 v[176:179], v118 offset:4608
	ds_read_b128 v[180:183], v118 offset:4672
	ds_read_b128 v[184:187], v118 offset:6912
	ds_read_b128 v[188:191], v118 offset:6976
	v_add_u32_e32 v0, s43, v120
	v_cvt_f32_i32_e32 v2, v0
	s_mov_b32 s4, 2.0
	s_mov_b32 s5, 0x40400000
	v_mul_f32_e64 v0, -v96, v2
	v_mov_b32_e32 v76, v0
	v_fma_f32 v77, -v96, v2, v96
	v_fmac_f32_e32 v76, 0, v96
	v_fma_f32 v78, v96, s4, v0
	v_fma_f32 v79, v97, s5, v0
	s_mov_b32 s4, 0x41800000
	s_mov_b32 s5, 0x41880000
	s_waitcnt lgkmcnt(7)
	v_mfma_f32_16x16x32_bf16 v[76:79], v[160:163], v[4:7], v[76:79]
	v_fma_f32 v82, v108, s90, v0
	v_fma_f32 v83, v109, s91, v0
	v_fma_f32 v80, v106, s4, v0
	v_fma_f32 v81, v107, s5, v0
	v_fma_f32 v130, v108, s92, v0
	v_fma_f32 v131, v109, s93, v0
	s_waitcnt lgkmcnt(6)
	v_mfma_f32_16x16x32_bf16 v[88:91], v[164:167], v[8:11], v[76:79]
	ds_read_b128 v[196:199], v243
	ds_read_b128 v[200:203], v243 offset:64
	s_nop 2
	v_fma_f32 v128, v106, s34, v0
	v_fma_f32 v129, v107, s35, v0
	v_fma_f32 v134, v108, s22, v0
	v_fma_f32 v135, v109, s23, v0
	s_waitcnt lgkmcnt(7)
	v_mfma_f32_16x16x32_bf16 v[76:79], v[168:171], v[4:7], v[80:83]
	s_nop 2
	v_fma_f32 v132, v106, s72, v0
	v_fma_f32 v133, v107, s73, v0
	v_max3_f32 v0, v88, s36, v89
	s_waitcnt lgkmcnt(6)
	v_mfma_f32_16x16x32_bf16 v[84:87], v[172:175], v[8:11], v[76:79]
	ds_read_b128 v[204:207], v243 offset:2304
	ds_read_b128 v[208:211], v243 offset:2368
	s_nop 2
	v_max3_f32 v0, v0, v90, v91
	s_waitcnt lgkmcnt(7)
	v_mfma_f32_16x16x32_bf16 v[76:79], v[176:179], v[4:7], v[128:131]
	s_nop 2
	v_max3_f32 v0, v0, v84, v85
	v_max3_f32 v0, v0, v86, v87
	s_waitcnt lgkmcnt(6)
	v_mfma_f32_16x16x32_bf16 v[76:79], v[180:183], v[8:11], v[76:79]
	ds_read_b128 v[212:215], v243 offset:4608
	ds_read_b128 v[216:219], v243 offset:4672
	s_waitcnt lgkmcnt(7)
	v_mfma_f32_16x16x32_bf16 v[80:83], v[184:187], v[4:7], v[132:135]
	s_nop 4
	v_max3_f32 v0, v0, v76, v77
	v_max3_f32 v0, v0, v78, v79
	s_waitcnt lgkmcnt(6)
	v_mfma_f32_16x16x32_bf16 v[80:83], v[188:191], v[8:11], v[80:83]
	ds_read_b128 v[220:223], v243 offset:6912
	ds_read_b128 v[224:227], v243 offset:6976
	s_nop 7
	v_max3_f32 v0, v0, v80, v81
	v_max3_f32 v0, v0, v82, v83
	v_cmp_gt_f32_e32 vcc, v0, v126
	s_cbranch_vccz .LBB0_1027
	ds_bpermute_b32 v2, v115, v0
	v_max_f32_e32 v0, v0, v0
	s_waitcnt lgkmcnt(0)
	v_max_f32_e32 v2, v2, v2
	v_max_f32_e32 v0, v0, v2
	ds_bpermute_b32 v2, v114, v0
	s_waitcnt lgkmcnt(0)
	v_max3_f32 v2, v126, v0, v2
	v_sub_f32_e32 v0, v126, v2
	v_exp_f32_e32 v0, v0
	v_mov_b32_e32 v126, v2
	v_mul_f32_e32 v127, v127, v0
	v_pk_mul_f32 v[62:63], v[62:63], v[0:1] op_sel_hi:[1,0]
	v_pk_mul_f32 v[60:61], v[60:61], v[0:1] op_sel_hi:[1,0]
	v_pk_mul_f32 v[66:67], v[66:67], v[0:1] op_sel_hi:[1,0]
	v_pk_mul_f32 v[64:65], v[64:65], v[0:1] op_sel_hi:[1,0]
	v_pk_mul_f32 v[70:71], v[70:71], v[0:1] op_sel_hi:[1,0]
	v_pk_mul_f32 v[68:69], v[68:69], v[0:1] op_sel_hi:[1,0]
	v_pk_mul_f32 v[74:75], v[74:75], v[0:1] op_sel_hi:[1,0]
	v_pk_mul_f32 v[72:73], v[72:73], v[0:1] op_sel_hi:[1,0]

.LBB0_1029:
	s_and_b64 vcc, exec, s[4:5]
	s_cbranch_vccz .LBB0_1023
	ds_read_b128 v[160:163], v119
	ds_read_b128 v[164:167], v119 offset:64
	ds_read_b128 v[168:171], v119 offset:2304
	ds_read_b128 v[172:175], v119 offset:2368
	ds_read_b128 v[176:179], v119 offset:4608
	ds_read_b128 v[180:183], v119 offset:4672
	ds_read_b128 v[184:187], v119 offset:6912
	ds_read_b128 v[188:191], v119 offset:6976
	v_or_b32_e32 v3, s1, v98
	v_sub_u32_e32 v3, v103, v3
	v_cvt_f32_i32_e32 v3, v3
	s_mov_b32 s4, 2.0
	s_mov_b32 s5, 0x40400000
	v_mul_f32_e64 v68, -v96, v3
	v_fma_f32 v62, v96, s4, v68
	v_fma_f32 v63, v97, s5, v68
	s_mov_b32 s4, 0x41800000
	s_mov_b32 s5, 0x41880000
	v_mov_b32_e32 v60, v68
	v_fma_f32 v66, v108, s90, v68
	v_fma_f32 v67, v109, s91, v68
	v_fma_f32 v64, v106, s4, v68
	v_fma_f32 v65, v107, s5, v68
	v_fma_f32 v128, v108, s92, v68
	v_fma_f32 v129, v109, s93, v68
	v_fma_f32 v126, v106, s34, v68
	v_fma_f32 v127, v107, s35, v68
	v_fma_f32 v132, v108, s22, v68
	v_fma_f32 v133, v109, s23, v68
	v_fma_f32 v130, v106, s72, v68
	v_fma_f32 v131, v107, s73, v68
	v_fma_f32 v61, -v96, v3, v96
	v_fmac_f32_e32 v60, 0, v96
	s_nop 0
	s_waitcnt lgkmcnt(7)
	v_mfma_f32_16x16x32_bf16 v[60:63], v[160:163], v[4:7], v[60:63]
	s_waitcnt lgkmcnt(6)
	v_mfma_f32_16x16x32_bf16 v[72:75], v[164:167], v[8:11], v[60:63]
	ds_read_b128 v[196:199], v244
	ds_read_b128 v[200:203], v244 offset:64
	s_nop 4
	s_nop 1
	v_max3_f32 v3, v72, s36, v73
	s_waitcnt lgkmcnt(7)
	v_mfma_f32_16x16x32_bf16 v[60:63], v[168:171], v[4:7], v[64:67]
	s_nop 2
	v_max3_f32 v3, v3, v74, v75
	s_waitcnt lgkmcnt(6)
	v_mfma_f32_16x16x32_bf16 v[68:71], v[172:175], v[8:11], v[60:63]
	ds_read_b128 v[204:207], v244 offset:2304
	ds_read_b128 v[208:211], v244 offset:2368
	s_nop 2
	s_nop 2
	v_max3_f32 v3, v3, v68, v69
	s_waitcnt lgkmcnt(7)
	v_mfma_f32_16x16x32_bf16 v[60:63], v[176:179], v[4:7], v[126:129]
	s_nop 2
	v_max3_f32 v3, v3, v70, v71
	s_waitcnt lgkmcnt(6)
	v_mfma_f32_16x16x32_bf16 v[60:63], v[180:183], v[8:11], v[60:63]
	ds_read_b128 v[212:215], v244 offset:4608
	ds_read_b128 v[216:219], v244 offset:4672
	s_waitcnt lgkmcnt(7)
	v_mfma_f32_16x16x32_bf16 v[64:67], v[184:187], v[4:7], v[130:133]
	s_nop 4
	v_max3_f32 v3, v3, v60, v61
	v_max3_f32 v3, v3, v62, v63
	s_waitcnt lgkmcnt(6)
	v_mfma_f32_16x16x32_bf16 v[64:67], v[188:191], v[8:11], v[64:67]
	ds_read_b128 v[220:223], v244 offset:6912
	ds_read_b128 v[224:227], v244 offset:6976
	s_nop 7
	v_max3_f32 v3, v3, v64, v65
	v_max3_f32 v3, v3, v66, v67
	v_cmp_gt_f32_e32 vcc, v3, v0
	s_cbranch_vccz .LBB0_1032
	ds_bpermute_b32 v126, v115, v3
	v_max_f32_e32 v3, v3, v3
	s_waitcnt lgkmcnt(0)
	v_max_f32_e32 v126, v126, v126
	v_max_f32_e32 v3, v3, v126
	ds_bpermute_b32 v126, v114, v3
	s_waitcnt lgkmcnt(0)
	v_max3_f32 v3, v0, v3, v126
	v_sub_f32_e32 v0, v0, v3
	v_exp_f32_e32 v0, v0
	s_nop 0
	v_mul_f32_e32 v2, v2, v0
	v_pk_mul_f32 v[78:79], v[78:79], v[0:1] op_sel_hi:[1,0]
	v_pk_mul_f32 v[76:77], v[76:77], v[0:1] op_sel_hi:[1,0]
	v_pk_mul_f32 v[82:83], v[82:83], v[0:1] op_sel_hi:[1,0]
	v_pk_mul_f32 v[80:81], v[80:81], v[0:1] op_sel_hi:[1,0]
	v_pk_mul_f32 v[86:87], v[86:87], v[0:1] op_sel_hi:[1,0]
	v_pk_mul_f32 v[84:85], v[84:85], v[0:1] op_sel_hi:[1,0]
	v_pk_mul_f32 v[90:91], v[90:91], v[0:1] op_sel_hi:[1,0]
	v_pk_mul_f32 v[88:89], v[88:89], v[0:1] op_sel_hi:[1,0]
	v_mov_b32_e32 v0, v3
